# attention interior loop: o/l rescale only when a row max rises more than 40 log2 units above the reference (wave-uniform skip of the 64 v_mul otherwise)
# speedup vs baseline: 1.0038x; 1.0038x over previous
.LBB0_162:
	v_add_u32_e32 v102, s15, v231
	ds_read_b128 v[22:25], v102
	ds_read_b128 v[26:29], v102 offset:32
	ds_read_b128 v[240:243], v102 offset:64
	ds_read_b128 v[244:247], v102 offset:96
	ds_read_b128 v[248:251], v102 offset:128
	ds_read_b128 v[130:133], v102 offset:160
	ds_read_b128 v[134:137], v102 offset:192
	ds_read_b128 v[104:107], v102 offset:224
	s_mul_i32 s14, s9, 0x5000
	s_addk_i32 s14, 0x3800
	s_cmp_lg_u32 s9, 0
	s_cselect_b32 s9, s14, 0x12800
	v_add_u32_e32 v233, s9, v232
	s_lshr_b32 s9, s5, 8
	v_lshrrev_b32_e32 v234, s9, v217
	v_and_b32_e32 v234, 1, v234
	v_cmp_eq_u32_e32 vcc, 1, v234
	s_add_i32 s5, s5, 64
	s_cmp_lg_u32 s4, s8
	v_cndmask_b32_e32 v234, v16, v14, vcc
	v_cndmask_b32_e64 v234, v234, v32, s[6:7]
	s_waitcnt lgkmcnt(7)
	v_mfma_f32_32x32x16_bf16 v[114:129], v[22:25], v[162:165], 0
	ds_read_b128 v[98:101], v102 offset:8704
	s_waitcnt lgkmcnt(7)
	v_mfma_f32_32x32x16_bf16 v[114:129], v[26:29], v[166:169], v[114:129]
	ds_read_b128 v[158:161], v102 offset:8736
	s_waitcnt lgkmcnt(7)
	v_mfma_f32_32x32x16_bf16 v[114:129], v[240:243], v[170:173], v[114:129]
	ds_read_b128 v[236:239], v102 offset:8768
	s_waitcnt lgkmcnt(7)
	v_mfma_f32_32x32x16_bf16 v[114:129], v[244:247], v[174:177], v[114:129]
	ds_read_b128 v[154:157], v102 offset:8800
	s_waitcnt lgkmcnt(7)
	v_mfma_f32_32x32x16_bf16 v[114:129], v[248:251], v[178:181], v[114:129]
	ds_read_b128 v[150:153], v102 offset:8832
	s_waitcnt lgkmcnt(7)
	v_mfma_f32_32x32x16_bf16 v[114:129], v[130:133], v[182:185], v[114:129]
	ds_read_b128 v[146:149], v102 offset:8864
	s_waitcnt lgkmcnt(7)
	v_mfma_f32_32x32x16_bf16 v[114:129], v[134:137], v[186:189], v[114:129]
	ds_read_b128 v[142:145], v102 offset:8896
	s_waitcnt lgkmcnt(7)
	v_mfma_f32_32x32x16_bf16 v[114:129], v[104:107], v[190:193], v[114:129]
	ds_read_b128 v[138:141], v102 offset:8928
	s_waitcnt lgkmcnt(7)
	v_mfma_f32_32x32x16_bf16 v[98:113], v[98:101], v[162:165], 0
	s_waitcnt lgkmcnt(6)
	v_mfma_f32_32x32x16_bf16 v[98:113], v[158:161], v[166:169], v[98:113]
	s_waitcnt lgkmcnt(5)
	v_mfma_f32_32x32x16_bf16 v[98:113], v[236:239], v[170:173], v[98:113]
	s_waitcnt lgkmcnt(4)
	v_mfma_f32_32x32x16_bf16 v[98:113], v[154:157], v[174:177], v[98:113]
	s_waitcnt lgkmcnt(3)
	v_mfma_f32_32x32x16_bf16 v[98:113], v[150:153], v[178:181], v[98:113]
	s_waitcnt lgkmcnt(2)
	v_mfma_f32_32x32x16_bf16 v[98:113], v[146:149], v[182:185], v[98:113]
	s_waitcnt lgkmcnt(1)
	v_mfma_f32_32x32x16_bf16 v[98:113], v[142:145], v[186:189], v[98:113]
	ds_read_b64_tr_b16 v[134:135], v233
	ds_read_b64_tr_b16 v[26:27], v233 offset:64
	ds_read_b64_tr_b16 v[130:131], v233 offset:128
	ds_read_b64_tr_b16 v[22:23], v233 offset:192
	ds_read_b64_tr_b16 v[136:137], v233 offset:2560
	ds_read_b64_tr_b16 v[28:29], v233 offset:2624
	ds_read_b64_tr_b16 v[132:133], v233 offset:2688
	ds_read_b128 v[240:243], v15
	ds_read_b128 v[248:251], v15 offset:32
	ds_read_b128 v[236:239], v15 offset:64
	ds_read_b128 v[154:157], v15 offset:96
	ds_read_b64_tr_b16 v[24:25], v233 offset:2752
	ds_read_b64_tr_b16 v[150:151], v233 offset:5120
	s_waitcnt lgkmcnt(13)
	v_mfma_f32_32x32x16_bf16 v[98:113], v[138:141], v[190:193], v[98:113]
	ds_read_b128 v[244:247], v15 offset:128
	ds_read_b128 v[158:161], v15 offset:160
	s_waitcnt lgkmcnt(7)
	s_waitcnt lgkmcnt(6)
	v_mfma_f32_32x32x16_bf16 v[34:49], v[134:137], v[18:21], v[34:49]
	s_waitcnt lgkmcnt(5)
	s_waitcnt lgkmcnt(4)
	v_fma_f32 v240, v114, s66, -v240
	v_fma_f32 v241, v115, s66, -v241
	v_fma_f32 v242, v116, s66, -v242
	v_fma_f32 v243, v117, s66, -v243
	v_fma_f32 v248, v118, s66, -v248
	v_fma_f32 v249, v119, s66, -v249
	v_fma_f32 v250, v120, s66, -v250
	v_fma_f32 v251, v121, s66, -v251
	v_fma_f32 v236, v122, s66, -v236
	v_fma_f32 v237, v123, s66, -v237
	v_fma_f32 v238, v124, s66, -v238
	v_fma_f32 v239, v125, s66, -v239
	v_fma_f32 v154, v126, s66, -v154
	v_fma_f32 v155, v127, s66, -v155
	v_fma_f32 v156, v128, s66, -v156
	v_fma_f32 v157, v129, s66, -v157
	ds_read_b64_tr_b16 v[122:123], v233 offset:5184
	ds_read_b64_tr_b16 v[126:127], v233 offset:5248
	ds_read_b64_tr_b16 v[114:115], v233 offset:5312
	ds_read_b64_tr_b16 v[152:153], v233 offset:7680
	ds_read_b64_tr_b16 v[124:125], v233 offset:7744
	ds_read_b64_tr_b16 v[128:129], v233 offset:7808
	ds_read_b64_tr_b16 v[116:117], v233 offset:7872
	ds_read_b128 v[118:121], v15 offset:192
	ds_read_b128 v[142:145], v15 offset:224
	s_waitcnt lgkmcnt(10)
	v_fma_f32 v245, v99, s66, -v245
	s_waitcnt lgkmcnt(9)
	s_waitcnt lgkmcnt(1)
	v_fma_f32 v244, v98, s66, -v244
	v_fma_f32 v246, v100, s66, -v246
	v_fma_f32 v247, v101, s66, -v247
	v_mfma_f32_32x32x16_bf16 v[66:81], v[130:133], v[18:21], v[66:81]
	v_max_f32_e32 v100, v241, v245
	v_fma_f32 v158, v102, s66, -v158
	v_fma_f32 v159, v103, s66, -v159
	v_fma_f32 v254, v108, s66, -v120
	v_max3_f32 v100, v240, v244, v100
	v_max_f32_e32 v101, v242, v246
	v_mfma_f32_32x32x16_bf16 v[34:49], v[150:153], v[10:13], v[34:49]
	v_max_f32_e32 v108, v243, v247
	v_fma_f32 v160, v104, s66, -v160
	v_fma_f32 v161, v105, s66, -v161
	v_max3_f32 v100, v100, v101, v108
	v_max_f32_e32 v101, v248, v158
	v_max_f32_e32 v108, v249, v159
	v_fma_f32 v252, v106, s66, -v118
	v_fma_f32 v253, v107, s66, -v119
	v_max3_f32 v100, v100, v101, v108
	v_max_f32_e32 v101, v250, v160
	v_max_f32_e32 v108, v251, v161
	s_waitcnt lgkmcnt(0)
	v_fma_f32 v225, v109, s66, -v121
	v_max3_f32 v100, v100, v101, v108
	v_max_f32_e32 v101, v236, v252
	v_max_f32_e32 v108, v237, v253
	v_fma_f32 v226, v110, s66, -v142
	v_fma_f32 v210, v111, s66, -v143
	v_max3_f32 v100, v100, v101, v108
	v_max_f32_e32 v101, v238, v254
	v_max_f32_e32 v108, v239, v225
	ds_read_b64_tr_b16 v[138:139], v233 offset:10240
	ds_read_b64_tr_b16 v[142:143], v233 offset:10304
	ds_read_b64_tr_b16 v[146:147], v233 offset:10368
	v_fma_f32 v211, v112, s66, -v144
	v_fma_f32 v212, v113, s66, -v145
	v_max3_f32 v100, v100, v101, v108
	v_max_f32_e32 v101, v154, v226
	v_max_f32_e32 v108, v155, v210
	ds_read_b64_tr_b16 v[118:119], v233 offset:10432
	ds_read_b64_tr_b16 v[140:141], v233 offset:12800
	ds_read_b64_tr_b16 v[144:145], v233 offset:12864
	ds_read_b64_tr_b16 v[148:149], v233 offset:12928
	ds_read_b64_tr_b16 v[120:121], v233 offset:12992
	v_max3_f32 v100, v100, v101, v108
	v_max_f32_e32 v101, v156, v211
	v_max_f32_e32 v108, v157, v212
	ds_read_b64_tr_b16 v[104:105], v233 offset:17920
	v_mfma_f32_32x32x16_bf16 v[66:81], v[126:129], v[10:13], v[66:81]
	v_max3_f32 v126, v100, v101, v108
	ds_bpermute_b32 v127, v31, v126
	ds_read_b64_tr_b16 v[102:103], v233 offset:15360
	ds_read_b64_tr_b16 v[106:107], v233 offset:15424
	ds_read_b64_tr_b16 v[110:111], v233 offset:15488
	ds_read_b64_tr_b16 v[98:99], v233 offset:15552
	ds_read_b64_tr_b16 v[108:109], v233 offset:17984
	ds_read_b64_tr_b16 v[112:113], v233 offset:18048
	ds_read_b64_tr_b16 v[100:101], v233 offset:18112
	v_add_u32_e32 v15, 0x100, v15
	s_waitcnt lgkmcnt(7)
	v_max_f32_e32 v126, v126, v127
	v_add_f32_e32 v126, v126, v234
	v_sub_f32_e32 v127, v126, v235
	v_cmp_lt_f32_e32 vcc, 0x42200000, v127
	s_nop 1
	s_mov_b64 s[94:95], vcc
	v_cndmask_b32_e32 v127, v235, v126, vcc
	v_mfma_f32_32x32x16_bf16 v[34:49], v[138:141], v[6:9], v[34:49]
	v_cmp_neq_f32_e32 vcc, s34, v127
	s_nop 1
	v_cndmask_b32_e32 v126, 0, v127, vcc
	v_sub_f32_e32 v131, v235, v126
	v_sub_f32_e32 v126, v126, v234
	v_mov_b32_e32 v234, v127
	v_sub_f32_e32 v127, v240, v126
	v_exp_f32_e32 v127, v127
	v_mfma_f32_32x32x16_bf16 v[82:97], v[26:29], v[18:21], v[82:97]
	v_sub_f32_e32 v26, v246, v126
	v_exp_f32_e32 v133, v26
	v_sub_f32_e32 v26, v243, v126
	v_exp_f32_e32 v134, v26
	v_sub_f32_e32 v26, v247, v126
	v_exp_f32_e32 v135, v26
	v_sub_f32_e32 v28, v159, v126
	s_waitcnt lgkmcnt(6)
	v_mfma_f32_32x32x16_bf16 v[34:49], v[102:105], v[2:5], v[34:49]
	v_sub_f32_e32 v102, v244, v126
	v_exp_f32_e32 v128, v102
	v_sub_f32_e32 v102, v241, v126
	v_exp_f32_e32 v129, v102
	v_sub_f32_e32 v102, v245, v126
	v_exp_f32_e32 v130, v102
	v_add_f32_e32 v102, v128, v127
	v_mfma_f32_32x32x16_bf16 v[82:97], v[122:125], v[10:13], v[82:97]
	v_add_f32_e32 v102, 0, v102
	v_add_f32_e32 v103, v130, v129
	v_add_f32_e32 v102, v103, v102
	v_sub_f32_e32 v103, v242, v126
	v_exp_f32_e32 v132, v103
	v_add_f32_e32 v27, v135, v134
	v_exp_f32_e32 v28, v28
	v_mfma_f32_32x32x16_bf16 v[66:81], v[146:149], v[6:9], v[66:81]
	v_add_f32_e32 v26, v133, v132
	v_add_f32_e32 v26, v26, v102
	v_sub_f32_e32 v102, v250, v126
	v_exp_f32_e32 v103, v102
	v_sub_f32_e32 v102, v160, v126
	v_exp_f32_e32 v105, v102
	v_sub_f32_e32 v102, v251, v126
	v_mfma_f32_32x32x16_bf16 v[82:97], v[142:145], v[6:9], v[82:97]
	v_sub_f32_e32 v104, v161, v126
	v_exp_f32_e32 v102, v102
	v_exp_f32_e32 v104, v104
	s_waitcnt lgkmcnt(1)
	v_mfma_f32_32x32x16_bf16 v[66:81], v[110:113], v[2:5], v[66:81]
	v_add_f32_e32 v110, v27, v26
	v_sub_f32_e32 v26, v248, v126
	v_exp_f32_e32 v27, v26
	v_sub_f32_e32 v26, v158, v126
	v_exp_f32_e32 v29, v26
	v_sub_f32_e32 v26, v249, v126
	v_exp_f32_e32 v26, v26
	v_mfma_f32_32x32x16_bf16 v[50:65], v[22:25], v[18:21], v[50:65]
	v_sub_f32_e32 v112, v225, v126
	v_exp_f32_e32 v112, v112
	v_sub_f32_e32 v18, v226, v126
	v_exp_f32_e32 v23, v18
	v_sub_f32_e32 v18, v155, v126
	v_mfma_f32_32x32x16_bf16 v[82:97], v[106:109], v[2:5], v[82:97]
	v_add_f32_e64 v106, v28, v26
	v_add_f32_e64 v107, v29, v27
	v_add_f32_e32 v107, v107, v110
	v_add_f32_e32 v108, v106, v107
	v_add_f32_e64 v106, v104, v102
	v_add_f32_e64 v107, v105, v103
	v_sub_f32_e32 v110, v238, v126
	v_add_f32_e32 v107, v107, v108
	v_mfma_f32_32x32x16_bf16 v[50:65], v[114:117], v[10:13], v[50:65]
	v_add_f32_e32 v124, v106, v107
	v_sub_f32_e32 v106, v236, v126
	v_exp_f32_e32 v107, v106
	v_sub_f32_e32 v106, v252, v126
	v_exp_f32_e32 v109, v106
	v_sub_f32_e32 v106, v237, v126
	v_sub_f32_e32 v108, v253, v126
	v_exp_f32_e32 v106, v106
	v_exp_f32_e32 v108, v108
	v_exp_f32_e32 v111, v110
	v_sub_f32_e32 v110, v254, v126
	v_exp_f32_e32 v113, v110
	v_sub_f32_e32 v110, v239, v126
	v_exp_f32_e32 v110, v110
	v_mfma_f32_32x32x16_bf16 v[50:65], v[118:121], v[6:9], v[50:65]
	v_add_f32_e64 v122, v108, v106
	v_add_f32_e64 v123, v109, v107
	v_sub_f32_e32 v10, v211, v126
	v_add_f32_e32 v123, v123, v124
	v_add_f32_e32 v124, v122, v123
	v_pk_add_f32 v[122:123], v[112:113], v[110:111]
	v_exp_f32_e32 v115, v10
	v_add_f32_e32 v123, v123, v124
	v_add_f32_e32 v124, v122, v123
	v_sub_f32_e32 v122, v154, v126
	v_exp_f32_e32 v123, v122
	v_exp_f32_e32 v122, v18
	v_sub_f32_e32 v18, v210, v126
	v_exp_f32_e32 v22, v18
	v_sub_f32_e32 v10, v157, v126
	v_sub_f32_e32 v18, v156, v126
	v_exp_f32_e32 v24, v10
	v_sub_f32_e32 v10, v212, v126
	s_waitcnt lgkmcnt(0)
	v_mfma_f32_32x32x16_bf16 v[50:65], v[98:101], v[2:5], v[50:65]
	v_exp_f32_e32 v25, v18
	v_exp_f32_e32 v114, v10
	v_pk_add_f32 v[6:7], v[22:23], v[122:123]
	v_exp_f32_e32 v116, v131
	v_add_f32_e32 v7, v7, v124
	v_add_f32_e32 v8, v6, v7
	v_pk_add_f32 v[6:7], v[114:115], v[24:25]
	v_add_f32_e32 v7, v7, v8
	v_add_f32_e32 v233, v6, v7
	v_fmac_f32_e32 v233, v33, v116
	s_mov_b64 vcc, s[94:95]
	s_nop 0
	s_cbranch_vccz .Lno_rescale
; #define ATT_QK(KOFF, X0, X1) { X0 = zero16(); X1 = zero16(); _Pragma("unroll") for (int kk = 0; kk < 8; ++kk) { \
;         const bf16x8 f0 = *(const LAS bf16x8*)(lds + (KOFF) + kroff + 32 * kk), f1 = *(const LAS bf16x8*)(lds + (KOFF) + kroff + 32 * KSTR + 32 * kk); \
;         X0 = mfma32(f0, qf[kk], X0); X1 = mfma32(f1, qf[kk], X1); } }
; __device__ __forceinline__ void attn_item(LAS unsigned char* lds, const bf16_t* Z, bf16_t* Y, const float* logf, const float* ksum, const float* rel_bias,
;                                           const int moba, const int b, const int h, const int qt) {
;     ...
;     const float lut128 = moba ? lut[128] : 0.f;
;     const int t_int = moba ? ((qt > 0) ? 4 * qt - 2 : 0) : 4 * qt;
;     int vcur = 0, t = 0;
;     if (t_int > 0) {
;         bf16x8 pq[4];
;         { f32x16 x0, x1; ATT_STAGE(0, KB_SZ, 1) ATT_QK(0, x0, x1) ATT_SMFAST(0, x0, x1, pq) }
;         vcur = 1; __syncthreads();
;         for (t = 1; t < t_int; ++t) {
;             const int kc = (t & 1) * KB_SZ, kn = KB_SZ - kc;
;             const int vnx = (vcur == 2) ? 0 : vcur + 1, vpv = (vcur == 0) ? 2 : vcur - 1;
;             ATT_STAGE(t, kn, vnx)
;             f32x16 x0, x1;
;             ATT_QK(kc, x0, x1)
;             ATT_PVALL(pq, V_BASE + vpv * VB_SZ)
;             ATT_SMFAST(64 * t, x0, x1, pq)
;             vcur = vnx; __syncthreads();
	v_mul_f32_e32 v48, v116, v48
	v_mul_f32_e32 v49, v116, v49
	v_mul_f32_e32 v46, v116, v46
	v_mul_f32_e32 v47, v116, v47
	v_mul_f32_e32 v44, v116, v44
	v_mul_f32_e32 v45, v116, v45
	v_mul_f32_e32 v42, v116, v42
	v_mul_f32_e32 v43, v116, v43
	v_mul_f32_e32 v40, v116, v40
	v_mul_f32_e32 v41, v116, v41
	v_mul_f32_e32 v38, v116, v38
	v_mul_f32_e32 v39, v116, v39
	v_mul_f32_e32 v36, v116, v36
	v_mul_f32_e32 v37, v116, v37
	v_mul_f32_e32 v34, v116, v34
	v_mul_f32_e32 v35, v116, v35
	v_mul_f32_e32 v96, v116, v96
	v_mul_f32_e32 v97, v116, v97
	v_mul_f32_e32 v94, v116, v94
	v_mul_f32_e32 v95, v116, v95
	v_mul_f32_e32 v92, v116, v92
	v_mul_f32_e32 v93, v116, v93
	v_mul_f32_e32 v90, v116, v90
	v_mul_f32_e32 v91, v116, v91
	v_mul_f32_e32 v88, v116, v88
	v_mul_f32_e32 v89, v116, v89
	v_mul_f32_e32 v86, v116, v86
	v_mul_f32_e32 v87, v116, v87
	v_mul_f32_e32 v84, v116, v84
	v_mul_f32_e32 v85, v116, v85
	v_mul_f32_e32 v82, v116, v82
	v_mul_f32_e32 v83, v116, v83
	v_mul_f32_e32 v80, v116, v80
	v_mul_f32_e32 v81, v116, v81
	v_mul_f32_e32 v78, v116, v78
	v_mul_f32_e32 v79, v116, v79
	v_mul_f32_e32 v76, v116, v76
	v_mul_f32_e32 v77, v116, v77
	v_mul_f32_e32 v74, v116, v74
	v_mul_f32_e32 v75, v116, v75
	v_mul_f32_e32 v72, v116, v72
	v_mul_f32_e32 v73, v116, v73
	v_mul_f32_e32 v70, v116, v70
	v_mul_f32_e32 v71, v116, v71
	v_mul_f32_e32 v68, v116, v68
	v_mul_f32_e32 v69, v116, v69
	v_mul_f32_e32 v66, v116, v66
	v_mul_f32_e32 v67, v116, v67
	v_mul_f32_e32 v64, v116, v64
	v_mul_f32_e32 v65, v116, v65
	v_mul_f32_e32 v62, v116, v62
	v_mul_f32_e32 v63, v116, v63
	v_mul_f32_e32 v60, v116, v60
	v_mul_f32_e32 v61, v116, v61
	v_mul_f32_e32 v58, v116, v58
	v_mul_f32_e32 v59, v116, v59
	v_mul_f32_e32 v56, v116, v56
	v_mul_f32_e32 v57, v116, v57
	v_mul_f32_e32 v54, v116, v54
	v_mul_f32_e32 v55, v116, v55
	v_mul_f32_e32 v52, v116, v52
	v_mul_f32_e32 v53, v116, v53
	v_mul_f32_e32 v50, v116, v50
	v_mul_f32_e32 v51, v116, v51
.Lno_rescale:
	v_cvt_pk_bf16_f32 v18, v127, v129
	v_cvt_pk_bf16_f32 v19, v132, v134
	v_cvt_pk_bf16_f32 v20, v27, v26
	v_cvt_pk_bf16_f32 v21, v103, v102
	v_cvt_pk_bf16_f32 v10, v107, v106
	v_cvt_pk_bf16_f32 v11, v111, v110
	v_cvt_pk_bf16_f32 v12, v123, v122
	v_cvt_pk_bf16_f32 v13, v25, v24
	v_cvt_pk_bf16_f32 v6, v128, v130
	v_cvt_pk_bf16_f32 v7, v133, v135
	v_cvt_pk_bf16_f32 v8, v29, v28
	v_cvt_pk_bf16_f32 v9, v105, v104
	v_cvt_pk_bf16_f32 v2, v109, v108
	v_cvt_pk_bf16_f32 v3, v113, v112
	v_cvt_pk_bf16_f32 v4, v23, v22
	v_cvt_pk_bf16_f32 v5, v115, v114
	s_barrier
	s_cbranch_scc0 .LBB0_167
	v_mov_b32_e32 v235, v234
	v_mov_b32_e32 v33, v233
	s_mov_b32 s9, s37
	s_mov_b32 s14, s8
	s_branch .LBB0_159
